# ssd_conv: 8 row loads per pass issued together (was load/wait/compute/store per row); phase 0: per-row scale loads issued with the data loads
# speedup vs baseline: 1.0053x; 1.0053x over previous
; #define LAS __attribute__((address_space(3)))
; DI void transpose_item(const Job& jb, int item, LAS float* scr, int lane) {
;     ...
;     for (int i = 0; i < 8; ++i) v[i] = ok ? __builtin_nontemporal_load((const f32x4*)(jb.src + (size_t)(k0 + 4 * i + kr) * jb.N + n0 + nl)) : (f32x4){0.f, 0.f, 0.f, 0.f};
; #pragma unroll
;     for (int i = 0; i < 8; ++i) { const int kk = 4 * i + kr; const float sc = jb.scale ? jb.scale[k0 + kk] : 1.f; LAS float* d = scr + kk * 65 + nl;
;         d[0] = v[i][0] * sc; d[1] = v[i][1] * sc; d[2] = v[i][2] * sc; d[3] = v[i][3] * sc; }
.LBB0_1007:
	s_or_b64 exec, exec, s[40:41]
	v_cndmask_b32_e64 v45, 0, 1, s[48:49]
	v_mov_b32_e32 v24, 1.0
	v_cmp_ne_u32_e64 s[40:41], 1, v45
	s_andn2_b64 vcc, exec, s[48:49]
	v_ashrrev_i32_e32 v45, 31, v44
	s_cbranch_vccnz .LBB0_1009
	v_lshl_add_u64 v[46:47], v[46:47], 2, s[44:45]
	global_load_dword v100, v[46:47], off
	global_load_dword v101, v[46:47], off offset:16
	global_load_dword v102, v[46:47], off offset:32
	global_load_dword v103, v[46:47], off offset:48
	global_load_dword v104, v[46:47], off offset:64
	global_load_dword v105, v[46:47], off offset:80
	global_load_dword v106, v[46:47], off offset:96
	global_load_dword v107, v[46:47], off offset:112
	s_waitcnt vmcnt(0)
	v_mov_b32_e32 v46, v100
	s_nop 0
	v_pk_mul_f32 v[30:31], v[30:31], v[46:47] op_sel_hi:[1,0]
	v_pk_mul_f32 v[32:33], v[32:33], v[46:47] op_sel_hi:[1,0]
	v_mov_b32_e32 v46, v101
	s_branch .LBB0_1010

; #define LAS __attribute__((address_space(3)))
; DI void transpose_item(const Job& jb, int item, LAS float* scr, int lane) {
;     ...
;     for (int i = 0; i < 8; ++i) v[i] = ok ? __builtin_nontemporal_load((const f32x4*)(jb.src + (size_t)(k0 + 4 * i + kr) * jb.N + n0 + nl)) : (f32x4){0.f, 0.f, 0.f, 0.f};
; #pragma unroll
;     for (int i = 0; i < 8; ++i) { const int kk = 4 * i + kr; const float sc = jb.scale ? jb.scale[k0 + kk] : 1.f; LAS float* d = scr + kk * 65 + nl;
;         d[0] = v[i][0] * sc; d[1] = v[i][1] * sc; d[2] = v[i][2] * sc; d[3] = v[i][3] * sc; }
.LBB0_1010:
	s_waitcnt vmcnt(0)
	ds_write2_b32 v53, v30, v31 offset1:1
	ds_write2_b32 v53, v32, v33 offset0:2 offset1:3
	v_pk_mul_f32 v[16:17], v[16:17], v[46:47] op_sel_hi:[1,0]
	v_add_u32_e32 v30, 0x410, v53
	ds_write2_b32 v30, v16, v17 offset1:1
	v_pk_mul_f32 v[16:17], v[18:19], v[46:47] op_sel_hi:[1,0]
	v_add_u32_e32 v18, 0x418, v53
	s_and_b64 vcc, exec, s[40:41]
	ds_write2_b32 v18, v16, v17 offset1:1
	s_cbranch_vccnz .LBB0_1012
	v_mov_b32_e32 v18, v102
	v_mov_b32_e32 v24, v103
	v_pk_mul_f32 v[26:27], v[26:27], v[18:19] op_sel_hi:[1,0]
	v_pk_mul_f32 v[28:29], v[28:29], v[18:19] op_sel_hi:[1,0]
.LBB0_1012:
	v_add_u32_e32 v16, 0x820, v53
	ds_write2_b32 v16, v26, v27 offset1:1
	v_add_u32_e32 v16, 0x828, v53
	ds_write2_b32 v16, v28, v29 offset1:1
	s_waitcnt vmcnt(0)
	v_pk_mul_f32 v[12:13], v[12:13], v[24:25] op_sel_hi:[1,0]
	v_add_u32_e32 v16, 0xc30, v53
	ds_write2_b32 v16, v12, v13 offset1:1
	v_pk_mul_f32 v[12:13], v[14:15], v[24:25] op_sel_hi:[1,0]
	v_add_u32_e32 v14, 0xc38, v53
	s_and_b64 vcc, exec, s[40:41]
	ds_write2_b32 v14, v12, v13 offset1:1
	s_cbranch_vccnz .LBB0_1014
	v_mov_b32_e32 v14, v104
	s_nop 0
	v_pk_mul_f32 v[20:21], v[20:21], v[14:15] op_sel_hi:[1,0]
	v_pk_mul_f32 v[22:23], v[22:23], v[14:15] op_sel_hi:[1,0]
	v_mov_b32_e32 v12, v105
	s_branch .LBB0_1015

; #define LAS __attribute__((address_space(3)))
; DI void transpose_item(const Job& jb, int item, LAS float* scr, int lane) {
;     ...
;     for (int i = 0; i < 8; ++i) v[i] = ok ? __builtin_nontemporal_load((const f32x4*)(jb.src + (size_t)(k0 + 4 * i + kr) * jb.N + n0 + nl)) : (f32x4){0.f, 0.f, 0.f, 0.f};
; #pragma unroll
;     for (int i = 0; i < 8; ++i) { const int kk = 4 * i + kr; const float sc = jb.scale ? jb.scale[k0 + kk] : 1.f; LAS float* d = scr + kk * 65 + nl;
;         d[0] = v[i][0] * sc; d[1] = v[i][1] * sc; d[2] = v[i][2] * sc; d[3] = v[i][3] * sc; }
.LBB0_1015:
	v_add_u32_e32 v13, 0x1040, v53
	ds_write2_b32 v13, v20, v21 offset1:1
	v_add_u32_e32 v13, 0x1048, v53
	ds_write2_b32 v13, v22, v23 offset1:1
	s_waitcnt vmcnt(0)
	v_pk_mul_f32 v[8:9], v[8:9], v[12:13] op_sel_hi:[1,0]
	v_add_u32_e32 v13, 0x1450, v53
	ds_write2_b32 v13, v8, v9 offset1:1
	v_pk_mul_f32 v[8:9], v[10:11], v[12:13] op_sel_hi:[1,0]
	v_add_u32_e32 v10, 0x1458, v53
	s_and_b64 vcc, exec, s[48:49]
	ds_write2_b32 v10, v8, v9 offset1:1
	s_cbranch_vccz .LBB0_1026
	v_mov_b32_e32 v10, v106
	v_mov_b32_e32 v8, v107
	v_pk_mul_f32 v[12:13], v[4:5], v[10:11] op_sel_hi:[1,0]
	v_pk_mul_f32 v[10:11], v[6:7], v[10:11] op_sel_hi:[1,0]
	s_cbranch_execnz .LBB0_1018

; DI unsigned pk2(float lo, float hi) { const f32x2v v = {lo, hi}; const bf16x2v b = __builtin_convertvector(v, bf16x2v); return __builtin_bit_cast(unsigned, b); }
; DI float siluf_(float x) { return x * sigmoidf_(x); }
; #define CONV_UNPK(W, D) do { const u32x4 w_ = (W); D[0] = (f32x4){bflo(w_.x), bfhi(w_.x), bflo(w_.y), bfhi(w_.y)}; D[1] = (f32x4){bflo(w_.z), bfhi(w_.z), bflo(w_.w), bfhi(w_.w)}; } while (0)
; DI void ssd_conv(const Params& P) {
;     ...
;             for (int r = 0; r < nrows; ++r) { const int row = row0 + r, t = t0 + r; f32x4 cur[2], acc[2]; CONV_UNPK(*(const u32x4*)(XBC + (size_t)row * 3072 + c8), cur);
; #pragma unroll
;                 for (int q = 0; q < 2; ++q) { acc[q] = cbv[q] + w[3][q] * cur[q] + w[2][q] * h1[q] + w[1][q] * h2[q] + w[0][q] * h3[q]; h3[q] = h2[q]; h2[q] = h1[q]; h1[q] = cur[q]; }
;                 u32x4 o; o.x = pk2(siluf_(acc[0][0]), siluf_(acc[0][1])); o.y = pk2(siluf_(acc[0][2]), siluf_(acc[0][3])); o.z = pk2(siluf_(acc[1][0]), siluf_(acc[1][1])); o.w = pk2(siluf_(acc[1][2]), siluf_(acc[1][3]));
;                 *(u32x4*)(XS + (size_t)row * 3072 + c8) = o;
;                 if (prompt && t >= 2045) { float* op = P.out + OUT_CONVP + ((size_t)b * 3 + (t - 2045)) * 3072 + c8; *(f32x4*)op = cur[0]; *(f32x4*)(op + 4) = cur[1]; }
;                 if (!prompt && t >= 1) { float* op = P.out + OUT_CONVS + ((size_t)b * 3 + (t - 1)) * 3072 + c8; *(f32x4*)op = cur[0]; *(f32x4*)(op + 4) = cur[1]; } }
.LBB0_1043:
	global_load_dwordx4 v[100:103], v[16:17], off
	s_add_i32 s18, s16, s17
	s_add_i32 s19, s18, 1
	v_mad_i64_i32 v[132:133], s[20:21], s19, v193, v[76:77]
	global_load_dwordx4 v[104:107], v[132:133], off
	s_add_i32 s19, s18, 2
	v_mad_i64_i32 v[132:133], s[20:21], s19, v193, v[76:77]
	global_load_dwordx4 v[108:111], v[132:133], off
	s_add_i32 s19, s18, 3
	v_mad_i64_i32 v[132:133], s[20:21], s19, v193, v[76:77]
	global_load_dwordx4 v[112:115], v[132:133], off
	s_add_i32 s19, s18, 4
	v_mad_i64_i32 v[132:133], s[20:21], s19, v193, v[76:77]
	global_load_dwordx4 v[116:119], v[132:133], off
	s_add_i32 s19, s18, 5
	v_mad_i64_i32 v[132:133], s[20:21], s19, v193, v[76:77]
	global_load_dwordx4 v[120:123], v[132:133], off
	s_add_i32 s19, s18, 6
	v_mad_i64_i32 v[132:133], s[20:21], s19, v193, v[76:77]
	global_load_dwordx4 v[124:127], v[132:133], off
	s_add_i32 s19, s18, 7
	v_mad_i64_i32 v[132:133], s[20:21], s19, v193, v[76:77]
	global_load_dwordx4 v[128:131], v[132:133], off
	s_waitcnt vmcnt(0)
	v_mov_b32_e32 v18, v100
	v_mov_b32_e32 v19, v101
	v_mov_b32_e32 v20, v102
	v_mov_b32_e32 v21, v103
	s_mov_b32 s18, 0x6300000
	v_lshlrev_b32_e32 v22, 16, v18
	v_and_b32_e32 v23, 0xffff0000, v18
	v_lshlrev_b32_e32 v82, 16, v19
	v_and_b32_e32 v83, 0xffff0000, v19
	v_pk_fma_f32 v[86:87], v[50:51], v[22:23], v[62:63]
	v_pk_fma_f32 v[88:89], v[52:53], v[82:83], v[64:65]
	v_pk_fma_f32 v[86:87], v[42:43], v[8:9], v[86:87]
	v_pk_fma_f32 v[88:89], v[44:45], v[10:11], v[88:89]
	v_lshlrev_b32_e32 v18, 16, v20
	v_and_b32_e32 v19, 0xffff0000, v20
	v_lshlrev_b32_e32 v20, 16, v21
	v_and_b32_e32 v21, 0xffff0000, v21
	v_pk_fma_f32 v[86:87], v[34:35], v[0:1], v[86:87]
	v_pk_fma_f32 v[88:89], v[36:37], v[2:3], v[88:89]
	v_pk_fma_f32 v[70:71], v[30:31], v[70:71], v[86:87]
	v_pk_fma_f32 v[72:73], v[32:33], v[72:73], v[88:89]
	v_pk_fma_f32 v[86:87], v[54:55], v[18:19], v[58:59]
	v_pk_fma_f32 v[88:89], v[56:57], v[20:21], v[60:61]
	v_pk_fma_f32 v[86:87], v[46:47], v[12:13], v[86:87]
	v_pk_fma_f32 v[88:89], v[48:49], v[14:15], v[88:89]
	v_pk_fma_f32 v[86:87], v[38:39], v[4:5], v[86:87]
	v_pk_fma_f32 v[88:89], v[40:41], v[6:7], v[88:89]
	s_nop 0
	v_pk_fma_f32 v[88:89], v[28:29], v[68:69], v[88:89]
	v_pk_fma_f32 v[68:69], v[26:27], v[66:67], v[86:87]
	v_mul_f32_e32 v66, 0xbfb8aa3b, v70
	v_mul_f32_e32 v67, 0xbfb8aa3b, v71
	v_exp_f32_e32 v66, v66
	v_exp_f32_e32 v67, v67
	v_add_f32_e32 v66, 1.0, v66
	v_add_f32_e32 v67, 1.0, v67
	v_rcp_f32_e32 v66, v66
	v_rcp_f32_e32 v67, v67
	s_nop 0
	v_pk_mul_f32 v[66:67], v[70:71], v[66:67]
	s_nop 0
	v_cvt_pk_bf16_f32 v66, v66, v67
	v_mul_f32_e32 v67, 0xbfb8aa3b, v72
	v_exp_f32_e32 v67, v67
	s_nop 0
	v_add_f32_e32 v67, 1.0, v67
	v_rcp_f32_e32 v70, v67
	v_mul_f32_e32 v67, 0xbfb8aa3b, v73
	v_exp_f32_e32 v67, v67
	s_nop 0
	v_add_f32_e32 v67, 1.0, v67
	v_rcp_f32_e32 v71, v67
	s_nop 0
	v_pk_mul_f32 v[70:71], v[72:73], v[70:71]
	s_nop 0
	v_cvt_pk_bf16_f32 v67, v70, v71
	v_mul_f32_e32 v70, 0xbfb8aa3b, v68
	v_mul_f32_e32 v71, 0xbfb8aa3b, v69
	v_exp_f32_e32 v70, v70
	v_exp_f32_e32 v71, v71
	v_add_f32_e32 v70, 1.0, v70
	v_add_f32_e32 v71, 1.0, v71
	v_rcp_f32_e32 v70, v70
	v_rcp_f32_e32 v71, v71
	s_nop 0
	v_pk_mul_f32 v[68:69], v[68:69], v[70:71]
	s_nop 0
	v_cvt_pk_bf16_f32 v68, v68, v69
	v_mul_f32_e32 v69, 0xbfb8aa3b, v88
	v_exp_f32_e32 v69, v69
	s_nop 0
	v_add_f32_e32 v69, 1.0, v69
	v_rcp_f32_e32 v70, v69
	v_mul_f32_e32 v69, 0xbfb8aa3b, v89
	v_exp_f32_e32 v69, v69
	s_nop 0
	v_add_f32_e32 v69, 1.0, v69
	v_rcp_f32_e32 v71, v69
	s_nop 0
	v_pk_mul_f32 v[70:71], v[88:89], v[70:71]
	s_nop 0
	v_cvt_pk_bf16_f32 v69, v70, v71
	v_add_co_u32_e32 v70, vcc, s18, v16
	s_add_i32 s18, s16, s17
	s_nop 0
	v_addc_co_u32_e32 v71, vcc, 0, v17, vcc
	s_add_i32 s19, s18, 1
	global_store_dwordx4 v[70:71], v[66:69], off
	s_nop 1
	v_mad_i64_i32 v[66:67], s[20:21], s19, v193, v[76:77]
	v_mov_b32_e32 v66, v104
	v_mov_b32_e32 v67, v105
	v_mov_b32_e32 v68, v106
	v_mov_b32_e32 v69, v107
	v_lshlrev_b32_e32 v70, 16, v66
	v_and_b32_e32 v71, 0xffff0000, v66
	v_pk_fma_f32 v[86:87], v[50:51], v[70:71], v[62:63]
	v_lshlrev_b32_e32 v72, 16, v67
	v_pk_fma_f32 v[86:87], v[42:43], v[22:23], v[86:87]
	v_and_b32_e32 v73, 0xffff0000, v67
	v_lshlrev_b32_e32 v66, 16, v68
	v_and_b32_e32 v67, 0xffff0000, v68
	v_pk_fma_f32 v[86:87], v[34:35], v[8:9], v[86:87]
	v_pk_fma_f32 v[88:89], v[52:53], v[72:73], v[64:65]
	v_pk_fma_f32 v[0:1], v[30:31], v[0:1], v[86:87]
	v_pk_fma_f32 v[86:87], v[54:55], v[66:67], v[58:59]
	v_pk_fma_f32 v[88:89], v[44:45], v[82:83], v[88:89]
	v_pk_fma_f32 v[86:87], v[46:47], v[18:19], v[86:87]
	v_pk_fma_f32 v[88:89], v[36:37], v[10:11], v[88:89]
	v_pk_fma_f32 v[86:87], v[38:39], v[12:13], v[86:87]
	v_pk_fma_f32 v[2:3], v[32:33], v[2:3], v[88:89]
	v_pk_fma_f32 v[4:5], v[26:27], v[4:5], v[86:87]
	v_mul_f32_e32 v86, 0xbfb8aa3b, v0
	v_mul_f32_e32 v87, 0xbfb8aa3b, v1
	v_exp_f32_e32 v86, v86
	v_exp_f32_e32 v87, v87
	v_lshlrev_b32_e32 v68, 16, v69
	v_and_b32_e32 v69, 0xffff0000, v69
	v_add_f32_e32 v86, 1.0, v86
	v_add_f32_e32 v87, 1.0, v87
	v_rcp_f32_e32 v86, v86
	v_rcp_f32_e32 v87, v87
	v_pk_fma_f32 v[88:89], v[56:57], v[68:69], v[60:61]
	v_pk_mul_f32 v[0:1], v[0:1], v[86:87]
	s_nop 0
	v_cvt_pk_bf16_f32 v0, v0, v1
	v_mul_f32_e32 v1, 0xbfb8aa3b, v2
	v_exp_f32_e32 v1, v1
	v_pk_fma_f32 v[88:89], v[48:49], v[20:21], v[88:89]
	v_add_f32_e32 v1, 1.0, v1
	v_rcp_f32_e32 v86, v1
	v_mul_f32_e32 v1, 0xbfb8aa3b, v3
	v_exp_f32_e32 v1, v1
	v_pk_fma_f32 v[88:89], v[40:41], v[14:15], v[88:89]
	v_add_f32_e32 v1, 1.0, v1
	v_rcp_f32_e32 v87, v1
	v_pk_fma_f32 v[6:7], v[28:29], v[6:7], v[88:89]
	v_pk_mul_f32 v[2:3], v[2:3], v[86:87]
	s_nop 0
	v_cvt_pk_bf16_f32 v1, v2, v3
	v_mul_f32_e32 v2, 0xbfb8aa3b, v4
; DI unsigned pk2(float lo, float hi) { const f32x2v v = {lo, hi}; const bf16x2v b = __builtin_convertvector(v, bf16x2v); return __builtin_bit_cast(unsigned, b); }
; DI float siluf_(float x) { return x * sigmoidf_(x); }
; #define CONV_UNPK(W, D) do { const u32x4 w_ = (W); D[0] = (f32x4){bflo(w_.x), bfhi(w_.x), bflo(w_.y), bfhi(w_.y)}; D[1] = (f32x4){bflo(w_.z), bfhi(w_.z), bflo(w_.w), bfhi(w_.w)}; } while (0)
; DI void ssd_conv(const Params& P) {
;     ...
;             for (int r = 0; r < nrows; ++r) { const int row = row0 + r, t = t0 + r; f32x4 cur[2], acc[2]; CONV_UNPK(*(const u32x4*)(XBC + (size_t)row * 3072 + c8), cur);
; #pragma unroll
;                 for (int q = 0; q < 2; ++q) { acc[q] = cbv[q] + w[3][q] * cur[q] + w[2][q] * h1[q] + w[1][q] * h2[q] + w[0][q] * h3[q]; h3[q] = h2[q]; h2[q] = h1[q]; h1[q] = cur[q]; }
;                 u32x4 o; o.x = pk2(siluf_(acc[0][0]), siluf_(acc[0][1])); o.y = pk2(siluf_(acc[0][2]), siluf_(acc[0][3])); o.z = pk2(siluf_(acc[1][0]), siluf_(acc[1][1])); o.w = pk2(siluf_(acc[1][2]), siluf_(acc[1][3]));
;                 *(u32x4*)(XS + (size_t)row * 3072 + c8) = o;
;                 if (prompt && t >= 2045) { float* op = P.out + OUT_CONVP + ((size_t)b * 3 + (t - 2045)) * 3072 + c8; *(f32x4*)op = cur[0]; *(f32x4*)(op + 4) = cur[1]; }
;                 if (!prompt && t >= 1) { float* op = P.out + OUT_CONVS + ((size_t)b * 3 + (t - 1)) * 3072 + c8; *(f32x4*)op = cur[0]; *(f32x4*)(op + 4) = cur[1]; } }
	v_mul_f32_e32 v3, 0xbfb8aa3b, v5
	v_exp_f32_e32 v2, v2
	v_exp_f32_e32 v3, v3
	v_add_f32_e32 v2, 1.0, v2
	v_add_f32_e32 v3, 1.0, v3
	v_rcp_f32_e32 v2, v2
	v_rcp_f32_e32 v3, v3
	s_nop 0
	v_pk_mul_f32 v[2:3], v[4:5], v[2:3]
	s_nop 0
	v_cvt_pk_bf16_f32 v2, v2, v3
	v_mul_f32_e32 v3, 0xbfb8aa3b, v6
	v_exp_f32_e32 v3, v3
	s_nop 0
	v_add_f32_e32 v3, 1.0, v3
	v_rcp_f32_e32 v4, v3
	v_mul_f32_e32 v3, 0xbfb8aa3b, v7
	v_exp_f32_e32 v3, v3
	s_nop 0
	v_add_f32_e32 v3, 1.0, v3
	v_rcp_f32_e32 v5, v3
	s_nop 0
	v_pk_mul_f32 v[4:5], v[6:7], v[4:5]
	s_nop 0
	v_cvt_pk_bf16_f32 v3, v4, v5
	v_mad_i64_i32 v[4:5], s[20:21], s19, v193, v[78:79]
	s_add_i32 s19, s18, 2
	global_store_dwordx4 v[4:5], v[0:3], off
	s_nop 1
	v_mad_i64_i32 v[0:1], s[20:21], s19, v193, v[76:77]
	v_mov_b32_e32 v0, v108
	v_mov_b32_e32 v1, v109
	v_mov_b32_e32 v2, v110
	v_mov_b32_e32 v3, v111
	v_lshlrev_b32_e32 v4, 16, v0
	v_and_b32_e32 v5, 0xffff0000, v0
	v_pk_fma_f32 v[86:87], v[50:51], v[4:5], v[62:63]
	v_lshlrev_b32_e32 v6, 16, v1
	v_pk_fma_f32 v[86:87], v[42:43], v[70:71], v[86:87]
	v_and_b32_e32 v7, 0xffff0000, v1
	v_lshlrev_b32_e32 v0, 16, v2
	v_and_b32_e32 v1, 0xffff0000, v2
	v_pk_fma_f32 v[86:87], v[34:35], v[22:23], v[86:87]
	v_pk_fma_f32 v[88:89], v[52:53], v[6:7], v[64:65]
	v_pk_fma_f32 v[8:9], v[30:31], v[8:9], v[86:87]
	v_pk_fma_f32 v[86:87], v[54:55], v[0:1], v[58:59]
	v_pk_fma_f32 v[88:89], v[44:45], v[72:73], v[88:89]
	v_pk_fma_f32 v[86:87], v[46:47], v[66:67], v[86:87]
	v_pk_fma_f32 v[88:89], v[36:37], v[82:83], v[88:89]
	v_pk_fma_f32 v[86:87], v[38:39], v[18:19], v[86:87]
	v_pk_fma_f32 v[10:11], v[32:33], v[10:11], v[88:89]
	v_pk_fma_f32 v[12:13], v[26:27], v[12:13], v[86:87]
	v_mul_f32_e32 v86, 0xbfb8aa3b, v8
	v_mul_f32_e32 v87, 0xbfb8aa3b, v9
	v_exp_f32_e32 v86, v86
	v_exp_f32_e32 v87, v87
	v_lshlrev_b32_e32 v2, 16, v3
	v_and_b32_e32 v3, 0xffff0000, v3
	v_add_f32_e32 v86, 1.0, v86
	v_add_f32_e32 v87, 1.0, v87
	v_rcp_f32_e32 v86, v86
	v_rcp_f32_e32 v87, v87
	v_pk_fma_f32 v[88:89], v[56:57], v[2:3], v[60:61]
	v_pk_mul_f32 v[8:9], v[8:9], v[86:87]
	s_nop 0
	v_cvt_pk_bf16_f32 v8, v8, v9
	v_mul_f32_e32 v9, 0xbfb8aa3b, v10
	v_exp_f32_e32 v9, v9
	v_pk_fma_f32 v[88:89], v[48:49], v[68:69], v[88:89]
	v_add_f32_e32 v9, 1.0, v9
	v_rcp_f32_e32 v86, v9
	v_mul_f32_e32 v9, 0xbfb8aa3b, v11
	v_exp_f32_e32 v9, v9
	v_pk_fma_f32 v[88:89], v[40:41], v[20:21], v[88:89]
	v_add_f32_e32 v9, 1.0, v9
	v_rcp_f32_e32 v87, v9
	v_pk_fma_f32 v[14:15], v[28:29], v[14:15], v[88:89]
	v_pk_mul_f32 v[10:11], v[10:11], v[86:87]
	s_nop 0
	v_cvt_pk_bf16_f32 v9, v10, v11
	v_mul_f32_e32 v10, 0xbfb8aa3b, v12
	v_mul_f32_e32 v11, 0xbfb8aa3b, v13
	v_exp_f32_e32 v10, v10
	v_exp_f32_e32 v11, v11
	v_add_f32_e32 v10, 1.0, v10
	v_add_f32_e32 v11, 1.0, v11
	v_rcp_f32_e32 v10, v10
	v_rcp_f32_e32 v11, v11
	s_nop 0
	v_pk_mul_f32 v[10:11], v[12:13], v[10:11]
	s_nop 0
	v_cvt_pk_bf16_f32 v10, v10, v11
	v_mul_f32_e32 v11, 0xbfb8aa3b, v14
	v_exp_f32_e32 v11, v11
	s_nop 0
	v_add_f32_e32 v11, 1.0, v11
	v_rcp_f32_e32 v12, v11
	v_mul_f32_e32 v11, 0xbfb8aa3b, v15
	v_exp_f32_e32 v11, v11
	s_nop 0
	v_add_f32_e32 v11, 1.0, v11
	v_rcp_f32_e32 v13, v11
	s_nop 0
	v_pk_mul_f32 v[12:13], v[14:15], v[12:13]
	s_nop 0
	v_cvt_pk_bf16_f32 v11, v12, v13
	v_mad_i64_i32 v[12:13], s[20:21], s19, v193, v[78:79]
	s_add_i32 s19, s18, 3
	global_store_dwordx4 v[12:13], v[8:11], off
	s_nop 1
	v_mad_i64_i32 v[8:9], s[20:21], s19, v193, v[76:77]
	v_mov_b32_e32 v8, v112
	v_mov_b32_e32 v9, v113
	v_mov_b32_e32 v10, v114
	v_mov_b32_e32 v11, v115
	v_lshlrev_b32_e32 v12, 16, v8
	v_and_b32_e32 v13, 0xffff0000, v8
	v_lshlrev_b32_e32 v14, 16, v9
	v_and_b32_e32 v15, 0xffff0000, v9
	v_pk_fma_f32 v[86:87], v[50:51], v[12:13], v[62:63]
	v_pk_fma_f32 v[88:89], v[52:53], v[14:15], v[64:65]
	v_pk_fma_f32 v[86:87], v[42:43], v[4:5], v[86:87]
	v_pk_fma_f32 v[88:89], v[44:45], v[6:7], v[88:89]
	v_lshlrev_b32_e32 v8, 16, v10
	v_and_b32_e32 v9, 0xffff0000, v10
	v_lshlrev_b32_e32 v10, 16, v11
	v_and_b32_e32 v11, 0xffff0000, v11
	v_pk_fma_f32 v[86:87], v[34:35], v[70:71], v[86:87]
	v_pk_fma_f32 v[88:89], v[36:37], v[72:73], v[88:89]
	v_pk_fma_f32 v[22:23], v[30:31], v[22:23], v[86:87]
	v_pk_fma_f32 v[82:83], v[32:33], v[82:83], v[88:89]
	v_pk_fma_f32 v[86:87], v[54:55], v[8:9], v[58:59]
	v_pk_fma_f32 v[88:89], v[56:57], v[10:11], v[60:61]
	v_pk_fma_f32 v[86:87], v[46:47], v[0:1], v[86:87]
	v_pk_fma_f32 v[88:89], v[48:49], v[2:3], v[88:89]
	v_pk_fma_f32 v[86:87], v[38:39], v[66:67], v[86:87]
	v_pk_fma_f32 v[88:89], v[40:41], v[68:69], v[88:89]
	s_nop 0
	v_pk_fma_f32 v[88:89], v[28:29], v[20:21], v[88:89]
	v_pk_fma_f32 v[20:21], v[26:27], v[18:19], v[86:87]
	v_mul_f32_e32 v18, 0xbfb8aa3b, v22
	v_mul_f32_e32 v19, 0xbfb8aa3b, v23
	v_exp_f32_e32 v18, v18
	v_exp_f32_e32 v19, v19
	v_add_f32_e32 v18, 1.0, v18
	v_add_f32_e32 v19, 1.0, v19
	v_rcp_f32_e32 v18, v18
	v_rcp_f32_e32 v19, v19
	s_nop 0
	v_pk_mul_f32 v[18:19], v[22:23], v[18:19]
	s_nop 0
	v_cvt_pk_bf16_f32 v18, v18, v19
	v_mul_f32_e32 v19, 0xbfb8aa3b, v82
	v_exp_f32_e32 v19, v19
	s_nop 0
	v_add_f32_e32 v19, 1.0, v19
	v_rcp_f32_e32 v22, v19
	v_mul_f32_e32 v19, 0xbfb8aa3b, v83
	v_exp_f32_e32 v19, v19
	s_nop 0
	v_add_f32_e32 v19, 1.0, v19
	v_rcp_f32_e32 v23, v19
	s_nop 0
	v_pk_mul_f32 v[22:23], v[82:83], v[22:23]
	s_nop 0
	v_cvt_pk_bf16_f32 v19, v22, v23
	v_mul_f32_e32 v22, 0xbfb8aa3b, v20
	v_mul_f32_e32 v23, 0xbfb8aa3b, v21
	v_exp_f32_e32 v22, v22
	v_exp_f32_e32 v23, v23
	v_add_f32_e32 v22, 1.0, v22
	v_add_f32_e32 v23, 1.0, v23
	v_rcp_f32_e32 v22, v22
	v_rcp_f32_e32 v23, v23
	s_nop 0
	v_pk_mul_f32 v[20:21], v[20:21], v[22:23]
	s_nop 0
	v_cvt_pk_bf16_f32 v20, v20, v21
	v_mul_f32_e32 v21, 0xbfb8aa3b, v88
	v_exp_f32_e32 v21, v21
	s_nop 0
; DI unsigned pk2(float lo, float hi) { const f32x2v v = {lo, hi}; const bf16x2v b = __builtin_convertvector(v, bf16x2v); return __builtin_bit_cast(unsigned, b); }
; DI float siluf_(float x) { return x * sigmoidf_(x); }
; #define CONV_UNPK(W, D) do { const u32x4 w_ = (W); D[0] = (f32x4){bflo(w_.x), bfhi(w_.x), bflo(w_.y), bfhi(w_.y)}; D[1] = (f32x4){bflo(w_.z), bfhi(w_.z), bflo(w_.w), bfhi(w_.w)}; } while (0)
; DI void ssd_conv(const Params& P) {
;     ...
;             for (int r = 0; r < nrows; ++r) { const int row = row0 + r, t = t0 + r; f32x4 cur[2], acc[2]; CONV_UNPK(*(const u32x4*)(XBC + (size_t)row * 3072 + c8), cur);
; #pragma unroll
;                 for (int q = 0; q < 2; ++q) { acc[q] = cbv[q] + w[3][q] * cur[q] + w[2][q] * h1[q] + w[1][q] * h2[q] + w[0][q] * h3[q]; h3[q] = h2[q]; h2[q] = h1[q]; h1[q] = cur[q]; }
;                 u32x4 o; o.x = pk2(siluf_(acc[0][0]), siluf_(acc[0][1])); o.y = pk2(siluf_(acc[0][2]), siluf_(acc[0][3])); o.z = pk2(siluf_(acc[1][0]), siluf_(acc[1][1])); o.w = pk2(siluf_(acc[1][2]), siluf_(acc[1][3]));
;                 *(u32x4*)(XS + (size_t)row * 3072 + c8) = o;
;                 if (prompt && t >= 2045) { float* op = P.out + OUT_CONVP + ((size_t)b * 3 + (t - 2045)) * 3072 + c8; *(f32x4*)op = cur[0]; *(f32x4*)(op + 4) = cur[1]; }
;                 if (!prompt && t >= 1) { float* op = P.out + OUT_CONVS + ((size_t)b * 3 + (t - 1)) * 3072 + c8; *(f32x4*)op = cur[0]; *(f32x4*)(op + 4) = cur[1]; } }
	v_add_f32_e32 v21, 1.0, v21
	v_rcp_f32_e32 v22, v21
	v_mul_f32_e32 v21, 0xbfb8aa3b, v89
	v_exp_f32_e32 v21, v21
	s_nop 0
	v_add_f32_e32 v21, 1.0, v21
	v_rcp_f32_e32 v23, v21
	s_nop 0
	v_pk_mul_f32 v[22:23], v[88:89], v[22:23]
	s_nop 0
	v_cvt_pk_bf16_f32 v21, v22, v23
	v_mad_i64_i32 v[22:23], s[20:21], s19, v193, v[78:79]
	s_add_i32 s19, s18, 4
	global_store_dwordx4 v[22:23], v[18:21], off
	s_nop 1
	v_mad_i64_i32 v[18:19], s[20:21], s19, v193, v[76:77]
	v_mov_b32_e32 v18, v116
	v_mov_b32_e32 v19, v117
	v_mov_b32_e32 v20, v118
	v_mov_b32_e32 v21, v119
	v_lshlrev_b32_e32 v22, 16, v18
	v_and_b32_e32 v23, 0xffff0000, v18
	v_lshlrev_b32_e32 v82, 16, v19
	v_and_b32_e32 v83, 0xffff0000, v19
	v_pk_fma_f32 v[86:87], v[50:51], v[22:23], v[62:63]
	v_pk_fma_f32 v[88:89], v[52:53], v[82:83], v[64:65]
	v_pk_fma_f32 v[86:87], v[42:43], v[12:13], v[86:87]
	v_pk_fma_f32 v[88:89], v[44:45], v[14:15], v[88:89]
	v_lshlrev_b32_e32 v18, 16, v20
	v_and_b32_e32 v19, 0xffff0000, v20
	v_lshlrev_b32_e32 v20, 16, v21
	v_and_b32_e32 v21, 0xffff0000, v21
	v_pk_fma_f32 v[86:87], v[34:35], v[4:5], v[86:87]
	v_pk_fma_f32 v[88:89], v[36:37], v[6:7], v[88:89]
	v_pk_fma_f32 v[70:71], v[30:31], v[70:71], v[86:87]
	v_pk_fma_f32 v[72:73], v[32:33], v[72:73], v[88:89]
	v_pk_fma_f32 v[86:87], v[54:55], v[18:19], v[58:59]
	v_pk_fma_f32 v[88:89], v[56:57], v[20:21], v[60:61]
	v_pk_fma_f32 v[86:87], v[46:47], v[8:9], v[86:87]
	v_pk_fma_f32 v[88:89], v[48:49], v[10:11], v[88:89]
	v_pk_fma_f32 v[86:87], v[38:39], v[0:1], v[86:87]
	v_pk_fma_f32 v[88:89], v[40:41], v[2:3], v[88:89]
	s_nop 0
	v_pk_fma_f32 v[88:89], v[28:29], v[68:69], v[88:89]
	v_pk_fma_f32 v[68:69], v[26:27], v[66:67], v[86:87]
	v_mul_f32_e32 v66, 0xbfb8aa3b, v70
	v_mul_f32_e32 v67, 0xbfb8aa3b, v71
	v_exp_f32_e32 v66, v66
	v_exp_f32_e32 v67, v67
	v_add_f32_e32 v66, 1.0, v66
	v_add_f32_e32 v67, 1.0, v67
	v_rcp_f32_e32 v66, v66
	v_rcp_f32_e32 v67, v67
	s_nop 0
	v_pk_mul_f32 v[66:67], v[70:71], v[66:67]
	s_nop 0
	v_cvt_pk_bf16_f32 v66, v66, v67
	v_mul_f32_e32 v67, 0xbfb8aa3b, v72
	v_exp_f32_e32 v67, v67
	s_nop 0
	v_add_f32_e32 v67, 1.0, v67
	v_rcp_f32_e32 v70, v67
	v_mul_f32_e32 v67, 0xbfb8aa3b, v73
	v_exp_f32_e32 v67, v67
	s_nop 0
	v_add_f32_e32 v67, 1.0, v67
	v_rcp_f32_e32 v71, v67
	s_nop 0
	v_pk_mul_f32 v[70:71], v[72:73], v[70:71]
	s_nop 0
	v_cvt_pk_bf16_f32 v67, v70, v71
	v_mul_f32_e32 v70, 0xbfb8aa3b, v68
	v_mul_f32_e32 v71, 0xbfb8aa3b, v69
	v_exp_f32_e32 v70, v70
	v_exp_f32_e32 v71, v71
	v_add_f32_e32 v70, 1.0, v70
	v_add_f32_e32 v71, 1.0, v71
	v_rcp_f32_e32 v70, v70
	v_rcp_f32_e32 v71, v71
	s_nop 0
	v_pk_mul_f32 v[68:69], v[68:69], v[70:71]
	s_nop 0
	v_cvt_pk_bf16_f32 v68, v68, v69
	v_mul_f32_e32 v69, 0xbfb8aa3b, v88
	v_exp_f32_e32 v69, v69
	s_nop 0
	v_add_f32_e32 v69, 1.0, v69
	v_rcp_f32_e32 v70, v69
	v_mul_f32_e32 v69, 0xbfb8aa3b, v89
	v_exp_f32_e32 v69, v69
	s_nop 0
	v_add_f32_e32 v69, 1.0, v69
	v_rcp_f32_e32 v71, v69
	s_nop 0
	v_pk_mul_f32 v[70:71], v[88:89], v[70:71]
	s_nop 0
	v_cvt_pk_bf16_f32 v69, v70, v71
	v_mad_i64_i32 v[70:71], s[20:21], s19, v193, v[78:79]
	s_add_i32 s20, s18, 5
	global_store_dwordx4 v[70:71], v[66:69], off
	s_add_i32 s19, s11, s17
	s_add_i32 s21, s19, 5
	v_mad_i64_i32 v[66:67], s[22:23], s20, v193, v[76:77]
	v_mov_b32_e32 v66, v120
	v_mov_b32_e32 v67, v121
	v_mov_b32_e32 v68, v122
	v_mov_b32_e32 v69, v123
	s_cmpk_lt_u32 s21, 0x7fd
	v_lshlrev_b32_e32 v70, 16, v66
	v_and_b32_e32 v71, 0xffff0000, v66
	v_lshlrev_b32_e32 v72, 16, v67
	v_and_b32_e32 v73, 0xffff0000, v67
	v_pk_fma_f32 v[86:87], v[50:51], v[70:71], v[62:63]
	v_pk_fma_f32 v[88:89], v[52:53], v[72:73], v[64:65]
	v_pk_fma_f32 v[86:87], v[42:43], v[22:23], v[86:87]
	v_pk_fma_f32 v[88:89], v[44:45], v[82:83], v[88:89]
	v_lshlrev_b32_e32 v66, 16, v68
	v_and_b32_e32 v67, 0xffff0000, v68
	v_lshlrev_b32_e32 v68, 16, v69
	v_and_b32_e32 v69, 0xffff0000, v69
	v_pk_fma_f32 v[86:87], v[34:35], v[12:13], v[86:87]
	v_pk_fma_f32 v[88:89], v[36:37], v[14:15], v[88:89]
	v_pk_fma_f32 v[4:5], v[30:31], v[4:5], v[86:87]
	v_pk_fma_f32 v[6:7], v[32:33], v[6:7], v[88:89]
	v_pk_fma_f32 v[86:87], v[54:55], v[66:67], v[58:59]
	v_pk_fma_f32 v[88:89], v[56:57], v[68:69], v[60:61]
	v_pk_fma_f32 v[86:87], v[46:47], v[18:19], v[86:87]
	v_pk_fma_f32 v[88:89], v[48:49], v[20:21], v[88:89]
	v_pk_fma_f32 v[86:87], v[38:39], v[8:9], v[86:87]
	v_pk_fma_f32 v[88:89], v[40:41], v[10:11], v[88:89]
	s_nop 0
	v_pk_fma_f32 v[88:89], v[28:29], v[2:3], v[88:89]
	v_pk_fma_f32 v[2:3], v[26:27], v[0:1], v[86:87]
	v_mul_f32_e32 v0, 0xbfb8aa3b, v4
	v_mul_f32_e32 v1, 0xbfb8aa3b, v5
	v_exp_f32_e32 v0, v0
	v_exp_f32_e32 v1, v1
	v_add_f32_e32 v0, 1.0, v0
	v_add_f32_e32 v1, 1.0, v1
	v_rcp_f32_e32 v0, v0
	v_rcp_f32_e32 v1, v1
	s_nop 0
	v_pk_mul_f32 v[0:1], v[4:5], v[0:1]
	s_nop 0
	v_cvt_pk_bf16_f32 v0, v0, v1
	v_mul_f32_e32 v1, 0xbfb8aa3b, v6
	v_exp_f32_e32 v1, v1
	s_nop 0
	v_add_f32_e32 v1, 1.0, v1
	v_rcp_f32_e32 v4, v1
	v_mul_f32_e32 v1, 0xbfb8aa3b, v7
	v_exp_f32_e32 v1, v1
	s_nop 0
	v_add_f32_e32 v1, 1.0, v1
	v_rcp_f32_e32 v5, v1
	s_nop 0
	v_pk_mul_f32 v[4:5], v[6:7], v[4:5]
	s_nop 0
	v_cvt_pk_bf16_f32 v1, v4, v5
	v_mul_f32_e32 v4, 0xbfb8aa3b, v2
	v_mul_f32_e32 v5, 0xbfb8aa3b, v3
	v_exp_f32_e32 v4, v4
	v_exp_f32_e32 v5, v5
	v_add_f32_e32 v4, 1.0, v4
	v_add_f32_e32 v5, 1.0, v5
	v_rcp_f32_e32 v4, v4
	v_rcp_f32_e32 v5, v5
	s_nop 0
	v_pk_mul_f32 v[2:3], v[2:3], v[4:5]
	s_nop 0
	v_cvt_pk_bf16_f32 v2, v2, v3
	v_mul_f32_e32 v3, 0xbfb8aa3b, v88
	v_exp_f32_e32 v3, v3
	s_nop 0
	v_add_f32_e32 v3, 1.0, v3
	v_rcp_f32_e32 v4, v3
	v_mul_f32_e32 v3, 0xbfb8aa3b, v89
	v_exp_f32_e32 v3, v3
	s_nop 0
	v_add_f32_e32 v3, 1.0, v3
	v_rcp_f32_e32 v5, v3
	s_nop 0
	v_pk_mul_f32 v[4:5], v[88:89], v[4:5]
	s_nop 0
	v_cvt_pk_bf16_f32 v3, v4, v5
	v_mad_i64_i32 v[4:5], s[22:23], s20, v193, v[78:79]
	global_store_dwordx4 v[4:5], v[0:3], off
	s_cbranch_scc1 .LBB0_1045
	s_load_dwordx2 s[20:21], s[0:1], 0x150
	s_add_i32 s22, s19, 0xfffff808
	s_add_u32 s22, s22, s8
	s_addc_u32 s23, 0, s9
	s_mulk_i32 s23, 0x3000
	s_mul_hi_u32 s25, s22, 0x3000
	s_add_i32 s25, s25, s23
	s_mulk_i32 s22, 0x3000
	s_waitcnt lgkmcnt(0)
	s_add_u32 s20, s20, s22
	s_addc_u32 s21, s21, s25
	v_lshl_add_u64 v[0:1], s[20:21], 0, v[24:25]
	s_mov_b64 s[20:21], 0x117f8000
	v_lshl_add_u64 v[2:3], v[0:1], 0, s[20:21]
	v_add_co_u32_e32 v0, vcc, 0x117f8000, v0
	s_nop 1
	v_addc_co_u32_e32 v1, vcc, 0, v1, vcc
	global_store_dwordx4 v[0:1], v[70:73], off
	global_store_dwordx4 v[2:3], v[66:69], off offset:16
; DI unsigned pk2(float lo, float hi) { const f32x2v v = {lo, hi}; const bf16x2v b = __builtin_convertvector(v, bf16x2v); return __builtin_bit_cast(unsigned, b); }
; DI float siluf_(float x) { return x * sigmoidf_(x); }
; #define CONV_UNPK(W, D) do { const u32x4 w_ = (W); D[0] = (f32x4){bflo(w_.x), bfhi(w_.x), bflo(w_.y), bfhi(w_.y)}; D[1] = (f32x4){bflo(w_.z), bfhi(w_.z), bflo(w_.w), bfhi(w_.w)}; } while (0)
; DI void ssd_conv(const Params& P) {
;     ...
;             for (int r = 0; r < nrows; ++r) { const int row = row0 + r, t = t0 + r; f32x4 cur[2], acc[2]; CONV_UNPK(*(const u32x4*)(XBC + (size_t)row * 3072 + c8), cur);
; #pragma unroll
;                 for (int q = 0; q < 2; ++q) { acc[q] = cbv[q] + w[3][q] * cur[q] + w[2][q] * h1[q] + w[1][q] * h2[q] + w[0][q] * h3[q]; h3[q] = h2[q]; h2[q] = h1[q]; h1[q] = cur[q]; }
;                 u32x4 o; o.x = pk2(siluf_(acc[0][0]), siluf_(acc[0][1])); o.y = pk2(siluf_(acc[0][2]), siluf_(acc[0][3])); o.z = pk2(siluf_(acc[1][0]), siluf_(acc[1][1])); o.w = pk2(siluf_(acc[1][2]), siluf_(acc[1][3]));
;                 *(u32x4*)(XS + (size_t)row * 3072 + c8) = o;
;                 if (prompt && t >= 2045) { float* op = P.out + OUT_CONVP + ((size_t)b * 3 + (t - 2045)) * 3072 + c8; *(f32x4*)op = cur[0]; *(f32x4*)(op + 4) = cur[1]; }
;                 if (!prompt && t >= 1) { float* op = P.out + OUT_CONVS + ((size_t)b * 3 + (t - 1)) * 3072 + c8; *(f32x4*)op = cur[0]; *(f32x4*)(op + 4) = cur[1]; } }
.LBB0_1045:
	s_add_i32 s21, s18, 6
	v_mad_i64_i32 v[0:1], s[22:23], s21, v193, v[76:77]
	v_mov_b32_e32 v4, v124
	v_mov_b32_e32 v5, v125
	v_mov_b32_e32 v6, v126
	v_mov_b32_e32 v7, v127
	s_add_i32 s20, s19, 6
	s_cmpk_lt_u32 s20, 0x7fd
	v_lshlrev_b32_e32 v0, 16, v4
	v_and_b32_e32 v1, 0xffff0000, v4
	v_lshlrev_b32_e32 v2, 16, v5
	v_and_b32_e32 v3, 0xffff0000, v5
	v_pk_fma_f32 v[86:87], v[50:51], v[0:1], v[62:63]
	v_pk_fma_f32 v[88:89], v[52:53], v[2:3], v[64:65]
	v_pk_fma_f32 v[86:87], v[42:43], v[70:71], v[86:87]
	v_pk_fma_f32 v[88:89], v[44:45], v[72:73], v[88:89]
	v_lshlrev_b32_e32 v4, 16, v6
	v_and_b32_e32 v5, 0xffff0000, v6
	v_lshlrev_b32_e32 v6, 16, v7
	v_and_b32_e32 v7, 0xffff0000, v7
	v_pk_fma_f32 v[86:87], v[34:35], v[22:23], v[86:87]
	v_pk_fma_f32 v[88:89], v[36:37], v[82:83], v[88:89]
	v_pk_fma_f32 v[12:13], v[30:31], v[12:13], v[86:87]
	v_pk_fma_f32 v[14:15], v[32:33], v[14:15], v[88:89]
	v_pk_fma_f32 v[86:87], v[54:55], v[4:5], v[58:59]
	v_pk_fma_f32 v[88:89], v[56:57], v[6:7], v[60:61]
	v_pk_fma_f32 v[86:87], v[46:47], v[66:67], v[86:87]
	v_pk_fma_f32 v[88:89], v[48:49], v[68:69], v[88:89]
	v_pk_fma_f32 v[86:87], v[38:39], v[18:19], v[86:87]
	v_pk_fma_f32 v[88:89], v[40:41], v[20:21], v[88:89]
	s_nop 0
	v_pk_fma_f32 v[88:89], v[28:29], v[10:11], v[88:89]
	v_pk_fma_f32 v[10:11], v[26:27], v[8:9], v[86:87]
	v_mul_f32_e32 v8, 0xbfb8aa3b, v12
	v_mul_f32_e32 v9, 0xbfb8aa3b, v13
	v_exp_f32_e32 v8, v8
	v_exp_f32_e32 v9, v9
	v_add_f32_e32 v8, 1.0, v8
	v_add_f32_e32 v9, 1.0, v9
	v_rcp_f32_e32 v8, v8
	v_rcp_f32_e32 v9, v9
	s_nop 0
	v_pk_mul_f32 v[8:9], v[12:13], v[8:9]
	s_nop 0
	v_cvt_pk_bf16_f32 v8, v8, v9
	v_mul_f32_e32 v9, 0xbfb8aa3b, v14
	v_exp_f32_e32 v9, v9
	s_nop 0
	v_add_f32_e32 v9, 1.0, v9
	v_rcp_f32_e32 v12, v9
	v_mul_f32_e32 v9, 0xbfb8aa3b, v15
	v_exp_f32_e32 v9, v9
	s_nop 0
	v_add_f32_e32 v9, 1.0, v9
	v_rcp_f32_e32 v13, v9
	s_nop 0
	v_pk_mul_f32 v[12:13], v[14:15], v[12:13]
	s_nop 0
	v_cvt_pk_bf16_f32 v9, v12, v13
	v_mul_f32_e32 v12, 0xbfb8aa3b, v10
	v_mul_f32_e32 v13, 0xbfb8aa3b, v11
	v_exp_f32_e32 v12, v12
	v_exp_f32_e32 v13, v13
	v_add_f32_e32 v12, 1.0, v12
	v_add_f32_e32 v13, 1.0, v13
	v_rcp_f32_e32 v12, v12
	v_rcp_f32_e32 v13, v13
	s_nop 0
	v_pk_mul_f32 v[10:11], v[10:11], v[12:13]
	s_nop 0
	v_cvt_pk_bf16_f32 v10, v10, v11
	v_mul_f32_e32 v11, 0xbfb8aa3b, v88
	v_exp_f32_e32 v11, v11
	s_nop 0
	v_add_f32_e32 v11, 1.0, v11
	v_rcp_f32_e32 v12, v11
	v_mul_f32_e32 v11, 0xbfb8aa3b, v89
	v_exp_f32_e32 v11, v11
	s_nop 0
	v_add_f32_e32 v11, 1.0, v11
	v_rcp_f32_e32 v13, v11
	s_nop 0
	v_pk_mul_f32 v[12:13], v[88:89], v[12:13]
	s_nop 0
	v_cvt_pk_bf16_f32 v11, v12, v13
	v_mad_i64_i32 v[12:13], s[22:23], s21, v193, v[78:79]
	global_store_dwordx4 v[12:13], v[8:11], off
	s_cbranch_scc1 .LBB0_1047
	s_load_dwordx2 s[20:21], s[0:1], 0x150
	s_add_i32 s22, s19, 0xfffff809
	s_add_u32 s22, s22, s8
	s_addc_u32 s23, 0, s9
	s_mulk_i32 s23, 0x3000
	s_mul_hi_u32 s25, s22, 0x3000
	s_add_i32 s25, s25, s23
	s_mulk_i32 s22, 0x3000
	s_waitcnt lgkmcnt(0)
	s_add_u32 s20, s20, s22
	s_addc_u32 s21, s21, s25
	v_lshl_add_u64 v[8:9], s[20:21], 0, v[24:25]
	s_mov_b64 s[20:21], 0x117f8000
	v_lshl_add_u64 v[10:11], v[8:9], 0, s[20:21]
	v_add_co_u32_e32 v8, vcc, 0x117f8000, v8
	s_nop 1
	v_addc_co_u32_e32 v9, vcc, 0, v9, vcc
	global_store_dwordx4 v[8:9], v[0:3], off
	global_store_dwordx4 v[10:11], v[4:7], off offset:16
.LBB0_1047:
	s_add_i32 s20, s18, 7
	v_mad_i64_i32 v[8:9], s[22:23], s20, v193, v[76:77]
	v_mov_b32_e32 v12, v128
	v_mov_b32_e32 v13, v129
	v_mov_b32_e32 v14, v130
	v_mov_b32_e32 v15, v131
	s_add_i32 s18, s19, 7
	s_cmpk_lt_u32 s18, 0x7fd
	v_lshlrev_b32_e32 v8, 16, v12
	v_and_b32_e32 v9, 0xffff0000, v12
	v_lshlrev_b32_e32 v10, 16, v13
	v_and_b32_e32 v11, 0xffff0000, v13
	v_pk_fma_f32 v[86:87], v[50:51], v[8:9], v[62:63]
	v_pk_fma_f32 v[88:89], v[52:53], v[10:11], v[64:65]
	v_pk_fma_f32 v[86:87], v[42:43], v[0:1], v[86:87]
	v_pk_fma_f32 v[88:89], v[44:45], v[2:3], v[88:89]
	v_lshlrev_b32_e32 v12, 16, v14
	v_and_b32_e32 v13, 0xffff0000, v14
	v_lshlrev_b32_e32 v14, 16, v15
	v_and_b32_e32 v15, 0xffff0000, v15
	v_pk_fma_f32 v[86:87], v[34:35], v[70:71], v[86:87]
	v_pk_fma_f32 v[88:89], v[36:37], v[72:73], v[88:89]
	v_pk_fma_f32 v[22:23], v[30:31], v[22:23], v[86:87]
	v_pk_fma_f32 v[82:83], v[32:33], v[82:83], v[88:89]
	v_pk_fma_f32 v[86:87], v[54:55], v[12:13], v[58:59]
	v_pk_fma_f32 v[88:89], v[56:57], v[14:15], v[60:61]
	v_pk_fma_f32 v[86:87], v[46:47], v[4:5], v[86:87]
	v_pk_fma_f32 v[88:89], v[48:49], v[6:7], v[88:89]
	v_pk_fma_f32 v[86:87], v[38:39], v[66:67], v[86:87]
	v_pk_fma_f32 v[88:89], v[40:41], v[68:69], v[88:89]
	s_nop 0
	v_pk_fma_f32 v[88:89], v[28:29], v[20:21], v[88:89]
	v_pk_fma_f32 v[20:21], v[26:27], v[18:19], v[86:87]
	v_mul_f32_e32 v18, 0xbfb8aa3b, v22
	v_mul_f32_e32 v19, 0xbfb8aa3b, v23
	v_exp_f32_e32 v18, v18
	v_exp_f32_e32 v19, v19
	v_add_f32_e32 v18, 1.0, v18
	v_add_f32_e32 v19, 1.0, v19
	v_rcp_f32_e32 v18, v18
	v_rcp_f32_e32 v19, v19
	s_nop 0
	v_pk_mul_f32 v[18:19], v[22:23], v[18:19]
	s_nop 0
	v_cvt_pk_bf16_f32 v18, v18, v19
	v_mul_f32_e32 v19, 0xbfb8aa3b, v82
	v_exp_f32_e32 v19, v19
	s_nop 0
	v_add_f32_e32 v19, 1.0, v19
	v_rcp_f32_e32 v22, v19
	v_mul_f32_e32 v19, 0xbfb8aa3b, v83
	v_exp_f32_e32 v19, v19
	s_nop 0
	v_add_f32_e32 v19, 1.0, v19
	v_rcp_f32_e32 v23, v19
	s_nop 0
	v_pk_mul_f32 v[22:23], v[82:83], v[22:23]
	s_nop 0
	v_cvt_pk_bf16_f32 v19, v22, v23
	v_mul_f32_e32 v22, 0xbfb8aa3b, v20
	v_mul_f32_e32 v23, 0xbfb8aa3b, v21
	v_exp_f32_e32 v22, v22
	v_exp_f32_e32 v23, v23
	v_add_f32_e32 v22, 1.0, v22
	v_add_f32_e32 v23, 1.0, v23
	v_rcp_f32_e32 v22, v22
	v_rcp_f32_e32 v23, v23
	s_nop 0
	v_pk_mul_f32 v[20:21], v[20:21], v[22:23]
	s_nop 0
	v_cvt_pk_bf16_f32 v20, v20, v21
	v_mul_f32_e32 v21, 0xbfb8aa3b, v88
	v_exp_f32_e32 v21, v21
	s_nop 0
	v_add_f32_e32 v21, 1.0, v21
	v_rcp_f32_e32 v22, v21
	v_mul_f32_e32 v21, 0xbfb8aa3b, v89
	v_exp_f32_e32 v21, v21
	s_nop 0
	v_add_f32_e32 v21, 1.0, v21
	v_rcp_f32_e32 v23, v21
	s_nop 0
	v_pk_mul_f32 v[22:23], v[88:89], v[22:23]
	s_nop 0
	v_cvt_pk_bf16_f32 v21, v22, v23
	v_mad_i64_i32 v[22:23], s[20:21], s20, v193, v[78:79]
	global_store_dwordx4 v[22:23], v[18:21], off
	s_cbranch_scc1 .LBB0_1042
	s_load_dwordx2 s[20:21], s[0:1], 0x150
	s_addk_i32 s19, 0xf80a
	s_add_u32 s18, s19, s8
	s_addc_u32 s19, 0, s9
	s_mulk_i32 s19, 0x3000
	s_mul_hi_u32 s22, s18, 0x3000
	s_add_i32 s22, s22, s19
	s_mulk_i32 s18, 0x3000
	s_waitcnt lgkmcnt(0)
	s_add_u32 s18, s20, s18
	s_addc_u32 s19, s21, s22
	v_lshl_add_u64 v[18:19], s[18:19], 0, v[24:25]
	s_mov_b64 s[18:19], 0x117f8000
	v_lshl_add_u64 v[20:21], v[18:19], 0, s[18:19]
	v_add_co_u32_e32 v18, vcc, 0x117f8000, v18
	s_nop 1
	v_addc_co_u32_e32 v19, vcc, 0, v19, vcc
	global_store_dwordx4 v[18:19], v[8:11], off
	global_store_dwordx4 v[20:21], v[12:15], off offset:16
	s_branch .LBB0_1042
